# baseline (speedup 1.0000x reference)
; __device__ __forceinline__ void peer_gather_phase(const Params& p, int layer, bool lat_only, char* smem, bool fuse_next, bool dry = false) {
;     ...
;     const int col = tid * 2;
;     const float* gate = mods + ((size_t)(layer * 33 + (l < LC ? 32 : b)) * 6 + 5) * 1024 + col;
;     float* xr = (l < LC) ? xc + ((size_t)b * LC + l) * D + col : lout + ((size_t)b * TL + (l - LC)) * D + col;
;     if (dry) xr = (float*)(lws + OFF_BONUS) + bid * 1024 + col;
;     float x[16];
;     unpack8(xa0, x);
;     unpack8(xa1, x + 8);
;     if (has_next) {
;       const size_t rown = (size_t)bn * LT + ln;
;       xa0 = gld_u4(act + rown * D + lane * 16);
;       xa1 = gld_u4(act + rown * D + lane * 16 + 8);
;     }
;     float d[16];
;     __builtin_amdgcn_sched_barrier(0);
;     DOT_U(0) DOT_U(1) DOT_U(2) DOT_U(3) DOT_U(4) DOT_U(5) DOT_U(6) DOT_U(7)
.LBB0_380:
	s_ashr_i32 s60, s77, 31
	s_cmpk_lt_i32 s77, 0x100
	s_cselect_b32 s26, 20, 23
	s_add_i32 s40, s77, 0xffffff00
	s_cmpk_lt_i32 s77, 0x100
	s_cselect_b32 s45, 32, s42
	s_cselect_b32 s44, s15, s75
	s_cselect_b32 s46, s14, s87
	s_cselect_b32 vcc_hi, s60, 0
	s_cselect_b32 vcc_lo, s77, s40
	s_add_i32 s45, s45, s81
	s_ashr_i32 s43, s42, 31
	s_mul_i32 s40, s45, 0x6000
	s_mul_hi_i32 s41, s45, 0x6000
	s_add_u32 s40, s16, s40
	s_addc_u32 s41, s17, s41
	v_lshlrev_b64 v[64:65], 2, v[130:131]
	v_lshl_add_u64 v[146:147], s[40:41], 0, v[64:65]
	s_lshl_b64 s[40:41], s[42:43], s26
	s_add_u32 s26, s46, s40
	s_addc_u32 s43, s44, s41
	s_lshl_b64 s[40:41], vcc, 12
	s_add_u32 s40, s26, s40
	s_addc_u32 s41, s43, s41
	v_lshl_add_u64 v[142:143], s[40:41], 0, v[64:65]
	s_waitcnt vmcnt(23)
	v_lshlrev_b32_e32 v145, 16, v59
	v_and_b32_e32 v144, 0xffff0000, v59
	s_waitcnt vmcnt(22)
	v_lshlrev_b32_e32 v166, 16, v60
	v_and_b32_e32 v164, 0xffff0000, v60
	v_lshlrev_b32_e32 v163, 16, v61
	v_and_b32_e32 v162, 0xffff0000, v61
	v_lshlrev_b32_e32 v161, 16, v62
	v_and_b32_e32 v160, 0xffff0000, v62
	v_lshlrev_b32_e32 v159, 16, v63
	v_and_b32_e32 v158, 0xffff0000, v63
	v_lshlrev_b32_e32 v157, 16, v56
	v_and_b32_e32 v156, 0xffff0000, v56
	v_lshlrev_b32_e32 v155, 16, v57
	v_and_b32_e32 v154, 0xffff0000, v57
	v_lshlrev_b32_e32 v153, 16, v58
	v_and_b32_e32 v152, 0xffff0000, v58
	s_waitcnt vmcnt(12)
	v_cvt_pk_f32_fp8_e32 v[56:57], v28
	v_cvt_pk_f32_fp8_sdwa v[58:59], v28 src0_sel:WORD_1
	v_cvt_pk_f32_fp8_e32 v[60:61], v29
	v_cvt_pk_f32_fp8_sdwa v[62:63], v29 src0_sel:WORD_1
	v_fma_f32 v151, v56, v166, 0
	v_fmac_f32_e32 v151, v57, v164
	v_cvt_pk_f32_fp8_e32 v[56:57], v24
	v_fmac_f32_e32 v151, v58, v163
	v_fmac_f32_e32 v151, v59, v162
	v_cvt_pk_f32_fp8_sdwa v[58:59], v24 src0_sel:WORD_1
	v_cvt_pk_f32_fp8_e32 v[64:65], v30
	v_fmac_f32_e32 v151, v60, v161
	v_fmac_f32_e32 v151, v61, v160
	v_cvt_pk_f32_fp8_e32 v[60:61], v25
	v_fma_f32 v165, v56, v166, 0
	v_cvt_pk_f32_fp8_sdwa v[66:67], v30 src0_sel:WORD_1
	v_fmac_f32_e32 v151, v62, v159
	v_fmac_f32_e32 v165, v57, v164
	v_cvt_pk_f32_fp8_e32 v[56:57], v20
	v_fmac_f32_e32 v151, v63, v158
	v_cvt_pk_f32_fp8_sdwa v[62:63], v25 src0_sel:WORD_1
	v_fmac_f32_e32 v165, v58, v163
	v_cvt_pk_f32_fp8_e32 v[68:69], v31
	v_fmac_f32_e32 v151, v64, v157
	v_fmac_f32_e32 v165, v59, v162
	v_cvt_pk_f32_fp8_sdwa v[58:59], v20 src0_sel:WORD_1
	v_fmac_f32_e32 v151, v65, v156
	v_cvt_pk_f32_fp8_e32 v[64:65], v26
	v_fmac_f32_e32 v165, v60, v161
	v_cvt_pk_f32_fp8_sdwa v[70:71], v31 src0_sel:WORD_1
	v_fmac_f32_e32 v151, v66, v155
	v_fmac_f32_e32 v165, v61, v160
	v_cvt_pk_f32_fp8_e32 v[60:61], v21
	v_fma_f32 v167, v56, v166, 0
	v_fmac_f32_e32 v151, v67, v154
	v_cvt_pk_f32_fp8_sdwa v[66:67], v26 src0_sel:WORD_1
	v_fmac_f32_e32 v165, v62, v159
	v_fmac_f32_e32 v167, v57, v164
	v_cvt_pk_f32_fp8_e32 v[56:57], v16
	v_fmac_f32_e32 v151, v68, v153
	v_fmac_f32_e32 v165, v63, v158
	v_cvt_pk_f32_fp8_sdwa v[62:63], v21 src0_sel:WORD_1
	v_fmac_f32_e32 v167, v58, v163
	v_fmac_f32_e32 v151, v69, v152
	v_cvt_pk_f32_fp8_e32 v[68:69], v27
	v_fmac_f32_e32 v165, v64, v157
	v_fmac_f32_e32 v167, v59, v162
	v_cvt_pk_f32_fp8_sdwa v[58:59], v16 src0_sel:WORD_1
	v_fmac_f32_e32 v151, v70, v145
	v_fmac_f32_e32 v165, v65, v156
	v_cvt_pk_f32_fp8_e32 v[64:65], v22
	v_fmac_f32_e32 v167, v60, v161
	v_fmac_f32_e32 v151, v71, v144
	v_cvt_pk_f32_fp8_sdwa v[70:71], v27 src0_sel:WORD_1
	v_fmac_f32_e32 v165, v66, v155
	v_fmac_f32_e32 v167, v61, v160
	v_cvt_pk_f32_fp8_e32 v[60:61], v17
	v_fma_f32 v168, v56, v166, 0
	v_fmac_f32_e32 v165, v67, v154
	v_cvt_pk_f32_fp8_sdwa v[66:67], v22 src0_sel:WORD_1
	v_fmac_f32_e32 v167, v62, v159
	v_fmac_f32_e32 v168, v57, v164
	v_cvt_pk_f32_fp8_e32 v[56:57], v12
	v_fmac_f32_e32 v165, v68, v153
	v_fmac_f32_e32 v167, v63, v158
	v_cvt_pk_f32_fp8_sdwa v[62:63], v17 src0_sel:WORD_1
	v_fmac_f32_e32 v168, v58, v163
	v_fmac_f32_e32 v165, v69, v152
	v_cvt_pk_f32_fp8_e32 v[68:69], v23
	v_fmac_f32_e32 v167, v64, v157
	v_fmac_f32_e32 v168, v59, v162
	v_cvt_pk_f32_fp8_sdwa v[58:59], v12 src0_sel:WORD_1
	v_fmac_f32_e32 v165, v70, v145
	v_fmac_f32_e32 v167, v65, v156
	v_cvt_pk_f32_fp8_e32 v[64:65], v18
	v_fmac_f32_e32 v168, v60, v161
	v_fmac_f32_e32 v165, v71, v144
	v_cvt_pk_f32_fp8_sdwa v[70:71], v23 src0_sel:WORD_1
	v_fmac_f32_e32 v167, v66, v155
	v_fmac_f32_e32 v168, v61, v160
	v_cvt_pk_f32_fp8_e32 v[60:61], v13
	v_fma_f32 v169, v56, v166, 0
	v_fmac_f32_e32 v167, v67, v154
	v_cvt_pk_f32_fp8_sdwa v[66:67], v18 src0_sel:WORD_1
	v_fmac_f32_e32 v168, v62, v159
	v_fmac_f32_e32 v169, v57, v164
	v_cvt_pk_f32_fp8_e32 v[56:57], v8
	v_fmac_f32_e32 v167, v68, v153
	v_fmac_f32_e32 v168, v63, v158
	v_cvt_pk_f32_fp8_sdwa v[62:63], v13 src0_sel:WORD_1
	v_fmac_f32_e32 v169, v58, v163
	v_fmac_f32_e32 v167, v69, v152
	v_cvt_pk_f32_fp8_e32 v[68:69], v19
	v_fmac_f32_e32 v168, v64, v157
	v_fmac_f32_e32 v169, v59, v162
	v_cvt_pk_f32_fp8_sdwa v[58:59], v8 src0_sel:WORD_1
	v_fmac_f32_e32 v167, v70, v145
	v_fmac_f32_e32 v168, v65, v156
	v_cvt_pk_f32_fp8_e32 v[64:65], v14
	v_fmac_f32_e32 v169, v60, v161
	v_fmac_f32_e32 v167, v71, v144
	v_cvt_pk_f32_fp8_sdwa v[70:71], v19 src0_sel:WORD_1
	v_fmac_f32_e32 v168, v66, v155
	v_fmac_f32_e32 v169, v61, v160
	v_cvt_pk_f32_fp8_e32 v[60:61], v9
	v_fma_f32 v170, v56, v166, 0
	v_fmac_f32_e32 v168, v67, v154
	v_cvt_pk_f32_fp8_sdwa v[66:67], v14 src0_sel:WORD_1
	v_fmac_f32_e32 v169, v62, v159
	v_fmac_f32_e32 v170, v57, v164
	v_cvt_pk_f32_fp8_e32 v[56:57], v4
	v_fmac_f32_e32 v168, v68, v153
	v_fmac_f32_e32 v169, v63, v158
	v_cvt_pk_f32_fp8_sdwa v[62:63], v9 src0_sel:WORD_1
	v_fmac_f32_e32 v170, v58, v163
	v_fmac_f32_e32 v168, v69, v152
	v_cvt_pk_f32_fp8_e32 v[68:69], v15
; #define LD_V(dst_, sl_, k_) dst_ = gld_u4(PV + (size_t)(unsigned)__builtin_amdgcn_readlane((int)(sl_).x, k_) * 1024 + lane * 16)
; __device__ __forceinline__ void peer_gather_phase(const Params& p, int layer, bool lat_only, char* smem, bool fuse_next, bool dry = false) {
;     ...
;     DOT_U(0) DOT_U(1) DOT_U(2) DOT_U(3) DOT_U(4) DOT_U(5) DOT_U(6) DOT_U(7)
;     __builtin_amdgcn_sched_barrier(0);
; #pragma unroll
;     for (int k = 4; k < 8; ++k) LD_V(va[k], sl, k);
;     __builtin_amdgcn_sched_barrier(0);
; #pragma unroll
;     for (int k = 0; k < 8; ++k) {
;       float u_[16];
;       unpack16_fp8(ub[k], u_);
;       float s_ = 0.f;
; #pragma unroll
;       for (int e = 0; e < 16; ++e) s_ += u_[e] * x[e];
;       d[8 + k] = s_;
;     }
	v_fmac_f32_e32 v169, v64, v157
	v_fmac_f32_e32 v170, v59, v162
	v_cvt_pk_f32_fp8_sdwa v[58:59], v4 src0_sel:WORD_1
	v_fmac_f32_e32 v168, v70, v145
	v_fmac_f32_e32 v169, v65, v156
	v_cvt_pk_f32_fp8_e32 v[64:65], v10
	v_fmac_f32_e32 v170, v60, v161
	v_fmac_f32_e32 v168, v71, v144
	v_cvt_pk_f32_fp8_sdwa v[70:71], v15 src0_sel:WORD_1
	v_fmac_f32_e32 v169, v66, v155
	v_fmac_f32_e32 v170, v61, v160
	v_cvt_pk_f32_fp8_e32 v[60:61], v5
	v_fma_f32 v171, v56, v166, 0
	v_fmac_f32_e32 v169, v67, v154
	v_cvt_pk_f32_fp8_sdwa v[66:67], v10 src0_sel:WORD_1
	v_fmac_f32_e32 v170, v62, v159
	v_fmac_f32_e32 v171, v57, v164
	v_cvt_pk_f32_fp8_e32 v[56:57], v0
	v_fmac_f32_e32 v169, v68, v153
	v_fmac_f32_e32 v170, v63, v158
	v_cvt_pk_f32_fp8_sdwa v[62:63], v5 src0_sel:WORD_1
	v_fmac_f32_e32 v171, v58, v163
	v_fmac_f32_e32 v169, v69, v152
	v_cvt_pk_f32_fp8_e32 v[68:69], v11
	v_fmac_f32_e32 v170, v64, v157
	v_fmac_f32_e32 v171, v59, v162
	v_cvt_pk_f32_fp8_sdwa v[58:59], v0 src0_sel:WORD_1
	v_fmac_f32_e32 v169, v70, v145
	v_fmac_f32_e32 v170, v65, v156
	v_cvt_pk_f32_fp8_e32 v[64:65], v6
	v_fmac_f32_e32 v171, v60, v161
	v_fmac_f32_e32 v169, v71, v144
	v_cvt_pk_f32_fp8_sdwa v[70:71], v11 src0_sel:WORD_1
	v_fmac_f32_e32 v170, v66, v155
	v_fmac_f32_e32 v171, v61, v160
	v_cvt_pk_f32_fp8_e32 v[60:61], v1
	v_fma_f32 v172, v56, v166, 0
	v_fmac_f32_e32 v170, v67, v154
	v_cvt_pk_f32_fp8_sdwa v[66:67], v6 src0_sel:WORD_1
	v_fmac_f32_e32 v171, v62, v159
	v_fmac_f32_e32 v172, v57, v164
	v_fmac_f32_e32 v170, v68, v153
	v_fmac_f32_e32 v171, v63, v158
	v_cvt_pk_f32_fp8_sdwa v[62:63], v1 src0_sel:WORD_1
	v_fmac_f32_e32 v172, v58, v163
	v_fmac_f32_e32 v170, v69, v152
	v_cvt_pk_f32_fp8_e32 v[68:69], v7
	v_fmac_f32_e32 v171, v64, v157
	v_fmac_f32_e32 v172, v59, v162
	v_fmac_f32_e32 v170, v70, v145
	v_fmac_f32_e32 v171, v65, v156
	v_cvt_pk_f32_fp8_e32 v[64:65], v2
	v_fmac_f32_e32 v172, v60, v161
	v_fmac_f32_e32 v170, v71, v144
	v_cvt_pk_f32_fp8_sdwa v[70:71], v7 src0_sel:WORD_1
	v_fmac_f32_e32 v171, v66, v155
	v_fmac_f32_e32 v172, v61, v160
	v_fmac_f32_e32 v171, v67, v154
	v_cvt_pk_f32_fp8_sdwa v[66:67], v2 src0_sel:WORD_1
	v_fmac_f32_e32 v172, v62, v159
	v_fmac_f32_e32 v171, v68, v153
	v_fmac_f32_e32 v172, v63, v158
	v_fmac_f32_e32 v171, v69, v152
	v_cvt_pk_f32_fp8_e32 v[68:69], v3
	v_fmac_f32_e32 v172, v64, v157
	v_fmac_f32_e32 v171, v70, v145
	v_fmac_f32_e32 v172, v65, v156
	v_fmac_f32_e32 v171, v71, v144
	v_cvt_pk_f32_fp8_sdwa v[70:71], v3 src0_sel:WORD_1
	v_fmac_f32_e32 v172, v66, v155
	v_fmac_f32_e32 v172, v67, v154
	v_fmac_f32_e32 v172, v68, v153
	v_fmac_f32_e32 v172, v69, v152
	v_fmac_f32_e32 v172, v70, v145
	v_fmac_f32_e32 v172, v71, v144
	v_readlane_b32 s26, v140, 4
	s_lshl_b64 s[40:41], s[26:27], 10
	v_readlane_b32 s26, v140, 5
	v_lshl_add_u64 v[56:57], v[126:127], 0, s[40:41]
	s_lshl_b64 s[40:41], s[26:27], 10
	v_readlane_b32 s26, v140, 6
	global_load_dwordx4 v[68:71], v[56:57], off
	v_lshl_add_u64 v[56:57], v[126:127], 0, s[40:41]
	s_lshl_b64 s[40:41], s[26:27], 10
	v_readlane_b32 s26, v140, 7
	global_load_dwordx4 v[64:67], v[56:57], off
	v_lshl_add_u64 v[56:57], v[126:127], 0, s[40:41]
	s_lshl_b64 s[40:41], s[26:27], 10
	global_load_dwordx4 v[60:63], v[56:57], off
	v_lshl_add_u64 v[56:57], v[126:127], 0, s[40:41]
	global_load_dwordx4 v[56:59], v[56:57], off
	s_waitcnt vmcnt(15)
	v_cvt_pk_f32_fp8_e32 v[174:175], v100
	v_cvt_pk_f32_fp8_sdwa v[176:177], v100 src0_sel:WORD_1
	v_cvt_pk_f32_fp8_e32 v[178:179], v101
	v_cvt_pk_f32_fp8_sdwa v[100:101], v101 src0_sel:WORD_1
	v_fma_f32 v173, v174, v166, 0
	v_fmac_f32_e32 v173, v175, v164
	v_fmac_f32_e32 v173, v176, v163
	v_fmac_f32_e32 v173, v177, v162
	v_cvt_pk_f32_fp8_e32 v[180:181], v102
	v_fmac_f32_e32 v173, v178, v161
	v_fmac_f32_e32 v173, v179, v160
	v_cvt_pk_f32_fp8_sdwa v[182:183], v102 src0_sel:WORD_1
	v_fmac_f32_e32 v173, v100, v159
	v_fmac_f32_e32 v173, v101, v158
	v_cvt_pk_f32_fp8_e32 v[184:185], v103
	v_fmac_f32_e32 v173, v180, v157
	v_fmac_f32_e32 v173, v181, v156
	v_cvt_pk_f32_fp8_sdwa v[102:103], v103 src0_sel:WORD_1
	v_fmac_f32_e32 v173, v182, v155
	v_fmac_f32_e32 v173, v183, v154
	v_fmac_f32_e32 v173, v184, v153
	v_fmac_f32_e32 v173, v185, v152
	s_waitcnt vmcnt(14)
	v_cvt_pk_f32_fp8_e32 v[100:101], v96
	v_fmac_f32_e32 v173, v102, v145
	v_fmac_f32_e32 v173, v103, v144
	v_cvt_pk_f32_fp8_sdwa v[102:103], v96 src0_sel:WORD_1
	v_cvt_pk_f32_fp8_e32 v[174:175], v97
	v_fma_f32 v182, v100, v166, 0
	v_fmac_f32_e32 v182, v101, v164
	v_cvt_pk_f32_fp8_sdwa v[96:97], v97 src0_sel:WORD_1
	v_fmac_f32_e32 v182, v102, v163
	v_fmac_f32_e32 v182, v103, v162
	v_cvt_pk_f32_fp8_e32 v[176:177], v98
	v_fmac_f32_e32 v182, v174, v161
	v_fmac_f32_e32 v182, v175, v160
	v_cvt_pk_f32_fp8_sdwa v[178:179], v98 src0_sel:WORD_1
	v_fmac_f32_e32 v182, v96, v159
	v_fmac_f32_e32 v182, v97, v158
	v_cvt_pk_f32_fp8_e32 v[180:181], v99
	v_fmac_f32_e32 v182, v176, v157
	v_fmac_f32_e32 v182, v177, v156
	v_cvt_pk_f32_fp8_sdwa v[98:99], v99 src0_sel:WORD_1
	v_fmac_f32_e32 v182, v178, v155
	v_fmac_f32_e32 v182, v179, v154
	v_fmac_f32_e32 v182, v180, v153
	v_fmac_f32_e32 v182, v181, v152
	s_waitcnt vmcnt(13)
	v_cvt_pk_f32_fp8_e32 v[96:97], v92
	v_fmac_f32_e32 v182, v98, v145
	v_fmac_f32_e32 v182, v99, v144
	v_cvt_pk_f32_fp8_sdwa v[98:99], v92 src0_sel:WORD_1
	v_cvt_pk_f32_fp8_e32 v[100:101], v93
	v_fma_f32 v178, v96, v166, 0
	v_fmac_f32_e32 v178, v97, v164
	v_cvt_pk_f32_fp8_sdwa v[92:93], v93 src0_sel:WORD_1
	v_fmac_f32_e32 v178, v98, v163
	v_fmac_f32_e32 v178, v99, v162
	v_cvt_pk_f32_fp8_e32 v[102:103], v94
	v_fmac_f32_e32 v178, v100, v161
	v_fmac_f32_e32 v178, v101, v160
	v_cvt_pk_f32_fp8_sdwa v[174:175], v94 src0_sel:WORD_1
	v_fmac_f32_e32 v178, v92, v159
	v_fmac_f32_e32 v178, v93, v158
	v_cvt_pk_f32_fp8_e32 v[176:177], v95
	v_fmac_f32_e32 v178, v102, v157
	v_fmac_f32_e32 v178, v103, v156
	v_cvt_pk_f32_fp8_sdwa v[94:95], v95 src0_sel:WORD_1
	v_fmac_f32_e32 v178, v174, v155
	v_fmac_f32_e32 v178, v175, v154
	v_fmac_f32_e32 v178, v176, v153
	v_fmac_f32_e32 v178, v177, v152
	s_waitcnt vmcnt(12)
; __device__ __forceinline__ void peer_gather_phase(const Params& p, int layer, bool lat_only, char* smem, bool fuse_next, bool dry = false) {
;     ...
; #pragma unroll
;     for (int k = 0; k < 8; ++k) {
;       float u_[16];
;       unpack16_fp8(ub[k], u_);
;       float s_ = 0.f;
; #pragma unroll
;       for (int e = 0; e < 16; ++e) s_ += u_[e] * x[e];
;       d[8 + k] = s_;
;     }
	v_cvt_pk_f32_fp8_e32 v[92:93], v88
	v_fmac_f32_e32 v178, v94, v145
	v_fmac_f32_e32 v178, v95, v144
	v_cvt_pk_f32_fp8_sdwa v[94:95], v88 src0_sel:WORD_1
	v_cvt_pk_f32_fp8_e32 v[96:97], v89
	v_fma_f32 v174, v92, v166, 0
	v_fmac_f32_e32 v174, v93, v164
	v_cvt_pk_f32_fp8_sdwa v[88:89], v89 src0_sel:WORD_1
	v_fmac_f32_e32 v174, v94, v163
	v_fmac_f32_e32 v174, v95, v162
	v_cvt_pk_f32_fp8_e32 v[98:99], v90
	v_fmac_f32_e32 v174, v96, v161
	v_fmac_f32_e32 v174, v97, v160
	v_cvt_pk_f32_fp8_sdwa v[100:101], v90 src0_sel:WORD_1
	v_fmac_f32_e32 v174, v88, v159
	v_fmac_f32_e32 v174, v89, v158
	v_cvt_pk_f32_fp8_e32 v[102:103], v91
	v_fmac_f32_e32 v174, v98, v157
	v_fmac_f32_e32 v174, v99, v156
	v_cvt_pk_f32_fp8_sdwa v[90:91], v91 src0_sel:WORD_1
	v_fmac_f32_e32 v174, v100, v155
	v_fmac_f32_e32 v174, v101, v154
	v_fmac_f32_e32 v174, v102, v153
	v_fmac_f32_e32 v174, v103, v152
	s_waitcnt vmcnt(11)
	v_cvt_pk_f32_fp8_e32 v[88:89], v84
	v_fmac_f32_e32 v174, v90, v145
	v_fmac_f32_e32 v174, v91, v144
	v_cvt_pk_f32_fp8_sdwa v[90:91], v84 src0_sel:WORD_1
	v_cvt_pk_f32_fp8_e32 v[92:93], v85
	v_fma_f32 v175, v88, v166, 0
	v_fmac_f32_e32 v175, v89, v164
	v_cvt_pk_f32_fp8_sdwa v[84:85], v85 src0_sel:WORD_1
	v_fmac_f32_e32 v175, v90, v163
	v_fmac_f32_e32 v175, v91, v162
	v_cvt_pk_f32_fp8_e32 v[94:95], v86
	v_fmac_f32_e32 v175, v92, v161
	v_fmac_f32_e32 v175, v93, v160
	v_cvt_pk_f32_fp8_sdwa v[96:97], v86 src0_sel:WORD_1
	v_fmac_f32_e32 v175, v84, v159
	v_fmac_f32_e32 v175, v85, v158
	v_cvt_pk_f32_fp8_e32 v[98:99], v87
	v_fmac_f32_e32 v175, v94, v157
	v_fmac_f32_e32 v175, v95, v156
	v_cvt_pk_f32_fp8_sdwa v[86:87], v87 src0_sel:WORD_1
	v_fmac_f32_e32 v175, v96, v155
	v_fmac_f32_e32 v175, v97, v154
	v_fmac_f32_e32 v175, v98, v153
	v_fmac_f32_e32 v175, v99, v152
	s_waitcnt vmcnt(10)
	v_cvt_pk_f32_fp8_e32 v[84:85], v80
	v_fmac_f32_e32 v175, v86, v145
	v_fmac_f32_e32 v175, v87, v144
	v_cvt_pk_f32_fp8_sdwa v[86:87], v80 src0_sel:WORD_1
	v_cvt_pk_f32_fp8_e32 v[88:89], v81
	v_fma_f32 v176, v84, v166, 0
	v_fmac_f32_e32 v176, v85, v164
	v_cvt_pk_f32_fp8_sdwa v[80:81], v81 src0_sel:WORD_1
	v_fmac_f32_e32 v176, v86, v163
	v_fmac_f32_e32 v176, v87, v162
	v_cvt_pk_f32_fp8_e32 v[90:91], v82
	v_fmac_f32_e32 v176, v88, v161
	v_fmac_f32_e32 v176, v89, v160
	v_cvt_pk_f32_fp8_sdwa v[92:93], v82 src0_sel:WORD_1
	v_fmac_f32_e32 v176, v80, v159
	v_fmac_f32_e32 v176, v81, v158
	v_cvt_pk_f32_fp8_e32 v[94:95], v83
	v_fmac_f32_e32 v176, v90, v157
	v_fmac_f32_e32 v176, v91, v156
	v_cvt_pk_f32_fp8_sdwa v[82:83], v83 src0_sel:WORD_1
	v_fmac_f32_e32 v176, v92, v155
	v_fmac_f32_e32 v176, v93, v154
	v_fmac_f32_e32 v176, v94, v153
	v_fmac_f32_e32 v176, v95, v152
	s_waitcnt vmcnt(9)
	v_cvt_pk_f32_fp8_e32 v[80:81], v76
	v_fmac_f32_e32 v176, v82, v145
	v_fmac_f32_e32 v176, v83, v144
	v_cvt_pk_f32_fp8_sdwa v[82:83], v76 src0_sel:WORD_1
	v_cvt_pk_f32_fp8_e32 v[84:85], v77
	v_fma_f32 v177, v80, v166, 0
	v_fmac_f32_e32 v177, v81, v164
	v_cvt_pk_f32_fp8_sdwa v[76:77], v77 src0_sel:WORD_1
	v_fmac_f32_e32 v177, v82, v163
	v_fmac_f32_e32 v177, v83, v162
	v_cvt_pk_f32_fp8_e32 v[86:87], v78
	v_fmac_f32_e32 v177, v84, v161
	v_fmac_f32_e32 v177, v85, v160
	v_cvt_pk_f32_fp8_sdwa v[88:89], v78 src0_sel:WORD_1
	v_fmac_f32_e32 v177, v76, v159
	v_fmac_f32_e32 v177, v77, v158
	v_cvt_pk_f32_fp8_e32 v[90:91], v79
	v_fmac_f32_e32 v177, v86, v157
	v_fmac_f32_e32 v177, v87, v156
	v_cvt_pk_f32_fp8_sdwa v[78:79], v79 src0_sel:WORD_1
	v_fmac_f32_e32 v177, v88, v155
	v_fmac_f32_e32 v177, v89, v154
	v_fmac_f32_e32 v177, v90, v153
	v_fmac_f32_e32 v177, v91, v152
	s_waitcnt vmcnt(8)
; #define LD_U(dst_, sl_, k_) dst_ = gld_u4(PU + (size_t)(unsigned)__builtin_amdgcn_readlane((int)(sl_).x, k_) * 1024 + lane * 16)
; #define LD_V(dst_, sl_, k_) dst_ = gld_u4(PV + (size_t)(unsigned)__builtin_amdgcn_readlane((int)(sl_).x, k_) * 1024 + lane * 16)
; __device__ __forceinline__ void peer_gather_phase(const Params& p, int layer, bool lat_only, char* smem, bool fuse_next, bool dry = false) {
;     ...
; #pragma unroll
;       for (int e = 0; e < 16; ++e) s_ += u_[e] * x[e];
;       d[8 + k] = s_;
;     }
;     __builtin_amdgcn_sched_barrier(0);
; #pragma unroll
;     for (int k = 0; k < 8; ++k) LD_V(vb[k], sl, 8 + k);
;     float2 xv = gld_f2(xr);
;     const float2 gt = gld_f2(gate);
;     __builtin_amdgcn_sched_barrier(0);
;     float n8[8], n4[4], n2[2], n1;
;     {
;       const bool h5 = (lane & 32) != 0, h4 = (lane & 16) != 0, h3 = (lane & 8) != 0, h2 = (lane & 4) != 0;
; #pragma unroll
;       for (int j = 0; j < 8; ++j) {
;         float snd = h5 ? d[j] : d[8 + j], kp = h5 ? d[8 + j] : d[j];
;         n8[j] = kp + __shfl_xor(snd, 32);
;       }
; #pragma unroll
;       for (int j = 0; j < 4; ++j) {
;         float snd = h4 ? n8[j] : n8[4 + j], kp = h4 ? n8[4 + j] : n8[j];
;         n4[j] = kp + __shfl_xor(snd, 16);
;       }
; #pragma unroll
;       for (int j = 0; j < 2; ++j) {
;         float snd = h3 ? n4[j] : n4[2 + j], kp = h3 ? n4[2 + j] : n4[j];
;         n2[j] = kp + __shfl_xor(snd, 8);
;       }
;       {
;         float snd = h2 ? n2[0] : n2[1], kp = h2 ? n2[1] : n2[0];
;         n1 = kp + __shfl_xor(snd, 4);
;       }
;       n1 = quad_sum(n1);
;     }
;     const float gk = __shfl(__uint_as_float(sl.y), lane >> 2);
;     const float coefl = gk * gelu_fast(n1 * (1.f / 64.f)) * (1.f / 8.f);
;     float acc[16];
; #pragma unroll
;     for (int e = 0; e < 16; ++e) acc[e] = 0.f;
; #pragma unroll
;     for (int k = 0; k < 8; ++k) {
;       const float ck = __int_as_float(__builtin_amdgcn_readlane(__float_as_int(coefl), 4 * k));
;       float v[16];
;       unpack16_fp8(va[k], v);
; #pragma unroll
;       for (int e = 0; e < 16; ++e) acc[e] += ck * v[e];
;     }
;     __builtin_amdgcn_sched_barrier(0);
;     if (has_next) {
; #pragma unroll
;       for (int k = 0; k < 8; ++k) LD_U(ua[k], sln, k);
	v_cvt_pk_f32_fp8_e32 v[76:77], v72
	v_fmac_f32_e32 v177, v78, v145
	v_fmac_f32_e32 v177, v79, v144
	v_cvt_pk_f32_fp8_sdwa v[78:79], v72 src0_sel:WORD_1
	v_cvt_pk_f32_fp8_e32 v[80:81], v73
	v_fma_f32 v166, v76, v166, 0
	v_fmac_f32_e32 v166, v77, v164
	v_cvt_pk_f32_fp8_sdwa v[72:73], v73 src0_sel:WORD_1
	v_fmac_f32_e32 v166, v78, v163
	v_fmac_f32_e32 v166, v79, v162
	v_cvt_pk_f32_fp8_e32 v[82:83], v74
	v_fmac_f32_e32 v166, v80, v161
	v_fmac_f32_e32 v166, v81, v160
	v_cvt_pk_f32_fp8_sdwa v[84:85], v74 src0_sel:WORD_1
	v_fmac_f32_e32 v166, v72, v159
	v_fmac_f32_e32 v166, v73, v158
	v_cvt_pk_f32_fp8_e32 v[86:87], v75
	v_fmac_f32_e32 v166, v82, v157
	v_fmac_f32_e32 v166, v83, v156
	v_cvt_pk_f32_fp8_sdwa v[74:75], v75 src0_sel:WORD_1
	v_fmac_f32_e32 v166, v84, v155
	v_fmac_f32_e32 v166, v85, v154
	v_fmac_f32_e32 v166, v86, v153
	v_fmac_f32_e32 v166, v87, v152
	v_fmac_f32_e32 v166, v74, v145
	v_fmac_f32_e32 v166, v75, v144
	v_readlane_b32 s26, v140, 8
	s_lshl_b64 s[40:41], s[26:27], 10
	v_readlane_b32 s26, v140, 9
	v_lshl_add_u64 v[72:73], v[126:127], 0, s[40:41]
	s_lshl_b64 s[40:41], s[26:27], 10
	v_readlane_b32 s26, v140, 10
	global_load_dwordx4 v[100:103], v[72:73], off
	v_lshl_add_u64 v[72:73], v[126:127], 0, s[40:41]
	s_lshl_b64 s[40:41], s[26:27], 10
	v_readlane_b32 s26, v140, 11
	global_load_dwordx4 v[96:99], v[72:73], off
	v_lshl_add_u64 v[72:73], v[126:127], 0, s[40:41]
	s_lshl_b64 s[40:41], s[26:27], 10
	v_readlane_b32 s26, v140, 12
	global_load_dwordx4 v[92:95], v[72:73], off
	v_lshl_add_u64 v[72:73], v[126:127], 0, s[40:41]
	s_lshl_b64 s[40:41], s[26:27], 10
	v_readlane_b32 s26, v140, 13
	global_load_dwordx4 v[88:91], v[72:73], off
	v_lshl_add_u64 v[72:73], v[126:127], 0, s[40:41]
	s_lshl_b64 s[40:41], s[26:27], 10
	v_readlane_b32 s26, v140, 14
	global_load_dwordx4 v[84:87], v[72:73], off
	v_lshl_add_u64 v[72:73], v[126:127], 0, s[40:41]
	s_lshl_b64 s[40:41], s[26:27], 10
	v_readlane_b32 s26, v140, 15
	global_load_dwordx4 v[80:83], v[72:73], off
	v_lshl_add_u64 v[72:73], v[126:127], 0, s[40:41]
	s_lshl_b64 s[40:41], s[26:27], 10
	s_movk_i32 s26, 0x5000
	v_add_co_u32_e32 v146, vcc, s26, v146
	global_load_dwordx4 v[76:79], v[72:73], off
	v_lshl_add_u64 v[72:73], v[126:127], 0, s[40:41]
	v_addc_co_u32_e32 v147, vcc, 0, v147, vcc
	global_load_dwordx4 v[72:75], v[72:73], off
	s_nop 0
	global_load_dwordx2 v[144:145], v[142:143], off
	s_nop 0
	global_load_dwordx2 v[146:147], v[146:147], off
	ds_bpermute_b32 v141, v148, v141
	v_permlane32_swap_b32_e32 v151, v173
	v_permlane32_swap_b32_e32 v165, v182
	v_permlane32_swap_b32_e32 v167, v178
	v_permlane32_swap_b32_e32 v168, v174
	v_permlane32_swap_b32_e32 v169, v175
	v_permlane32_swap_b32_e32 v170, v176
	v_permlane32_swap_b32_e32 v171, v177
	v_permlane32_swap_b32_e32 v172, v166
	v_add_f32_e32 v151, v151, v173
	v_add_f32_e32 v165, v165, v182
	v_add_f32_e32 v167, v167, v178
	v_add_f32_e32 v168, v168, v174
	v_add_f32_e32 v169, v169, v175
	v_add_f32_e32 v170, v170, v176
	v_add_f32_e32 v171, v171, v177
	v_add_f32_e32 v172, v172, v166
	v_permlane16_swap_b32_e32 v151, v169
	v_permlane16_swap_b32_e32 v165, v170
	v_permlane16_swap_b32_e32 v167, v171
	v_permlane16_swap_b32_e32 v168, v172
	v_add_f32_e32 v151, v151, v169
	v_add_f32_e32 v165, v165, v170
	v_add_f32_e32 v167, v167, v171
	v_add_f32_e32 v168, v168, v172
	v_cndmask_b32_e64 v173, v151, v167, s[6:7]
	v_cndmask_b32_e64 v174, v167, v151, s[6:7]
	v_cndmask_b32_e64 v175, v165, v168, s[6:7]
	v_cndmask_b32_e64 v176, v168, v165, s[6:7]
	v_add_f32_dpp v151, v173, v174 row_ror:8 row_mask:0xf bank_mask:0xf bound_ctrl:1
	v_add_f32_dpp v165, v175, v176 row_ror:8 row_mask:0xf bank_mask:0xf bound_ctrl:1
	v_cndmask_b32_e64 v173, v151, v165, s[8:9]
	v_cndmask_b32_e64 v174, v165, v151, s[8:9]
	s_nop 0
	v_mov_b32_dpp v175, v173 row_half_mirror row_mask:0xf bank_mask:0xf bound_ctrl:1
	s_nop 1
	v_add_f32_dpp v140, v175, v174 quad_perm:[3,2,1,0] row_mask:0xf bank_mask:0xf bound_ctrl:1
	s_waitcnt lgkmcnt(0)
	s_nop 1
	v_add_f32_dpp v140, v140, v140 quad_perm:[1,0,3,2] row_mask:0xf bank_mask:0xf bound_ctrl:1
	s_nop 1
	v_add_f32_dpp v140, v140, v140 quad_perm:[2,3,0,1] row_mask:0xf bank_mask:0xf bound_ctrl:1
	v_mul_f32_e32 v140, 0x3c800000, v140
	v_mul_f32_e32 v151, 0x3d372713, v140
	v_mul_f32_e32 v151, v140, v151
	v_fma_f32 v151, v140, v151, v140
	v_mul_f32_e32 v151, 0xbfcc422a, v151
	v_mul_f32_e32 v151, 0x3fb8aa3b, v151
	v_exp_f32_e32 v151, v151
	s_nop 0
	v_add_f32_e32 v151, 1.0, v151
	v_rcp_f32_e32 v151, v151
	s_nop 0
	v_mul_f32_e32 v140, v140, v151
	v_mul_f32_e32 v140, v140, v141
	v_mul_f32_e32 v140, 0x3e000000, v140
	s_nop 0
	v_readlane_b32 s90, v140, 0
	v_readlane_b32 s92, v140, 4
	v_readlane_b32 s44, v140, 8
	v_readlane_b32 s46, v140, 12
	v_readlane_b32 s80, v140, 16
	v_readlane_b32 s50, v140, 20
	v_readlane_b32 s74, v140, 24
	v_readlane_b32 s86, v140, 28
	s_and_b64 vcc, exec, s[12:13]
	s_cbranch_vccnz .LBB0_382
	s_waitcnt vmcnt(14)
	v_readlane_b32 s26, v138, 0
	s_lshl_b64 s[12:13], s[26:27], 10
	v_readlane_b32 s26, v138, 1
	v_lshl_add_u64 v[0:1], v[124:125], 0, s[12:13]
	s_lshl_b64 s[12:13], s[26:27], 10
	v_readlane_b32 s26, v138, 2
	global_load_dwordx4 v[28:31], v[0:1], off
	v_lshl_add_u64 v[0:1], v[124:125], 0, s[12:13]
	s_lshl_b64 s[12:13], s[26:27], 10
	v_readlane_b32 s26, v138, 3
	global_load_dwordx4 v[24:27], v[0:1], off
	v_lshl_add_u64 v[0:1], v[124:125], 0, s[12:13]
	s_lshl_b64 s[12:13], s[26:27], 10
	v_readlane_b32 s26, v138, 4
	global_load_dwordx4 v[20:23], v[0:1], off
	v_lshl_add_u64 v[0:1], v[124:125], 0, s[12:13]
	s_lshl_b64 s[12:13], s[26:27], 10
	v_readlane_b32 s26, v138, 5
	global_load_dwordx4 v[16:19], v[0:1], off
	v_lshl_add_u64 v[0:1], v[124:125], 0, s[12:13]
	s_lshl_b64 s[12:13], s[26:27], 10
	v_readlane_b32 s26, v138, 6
	global_load_dwordx4 v[12:15], v[0:1], off
	v_lshl_add_u64 v[0:1], v[124:125], 0, s[12:13]
	s_lshl_b64 s[12:13], s[26:27], 10
	v_readlane_b32 s26, v138, 7
	global_load_dwordx4 v[8:11], v[0:1], off
	v_lshl_add_u64 v[0:1], v[124:125], 0, s[12:13]
	s_lshl_b64 s[12:13], s[26:27], 10
	global_load_dwordx4 v[4:7], v[0:1], off
	v_lshl_add_u64 v[0:1], v[124:125], 0, s[12:13]
	global_load_dwordx4 v[0:3], v[0:1], off
